# weight-conversion transpose tiles: the four 16-byte loads of a tile issued together (own registers), counted vmcnt before the LDS writes, all 16 inlined copies
# speedup vs baseline: 1.0479x; 1.0038x over previous
.LBB0_62:
	s_andn2_b64 vcc, exec, s[14:15]
	s_cbranch_vccnz .LBB0_64
	s_add_i32 s20, s84, 0xffffeec0
	s_cmp_gt_u32 s20, 7
	s_cselect_b32 s2, 64, 0
	s_add_i32 s21, s84, 0xffffeeb8
	s_load_dwordx2 s[14:15], s[4:5], 0xc0
	s_cmp_lt_u32 s20, 8
	s_cselect_b32 s20, s20, s21
	s_lshl_b32 s20, s20, 6
	s_ashr_i32 s21, s20, 31
	v_mov_b32_e32 v14, v254
	s_lshl_b64 s[86:87], s[20:21], 2
	s_waitcnt lgkmcnt(0)
	s_add_u32 s14, s14, s86
	v_ashrrev_i32_e32 v2, 4, v14
	v_lshlrev_b32_e32 v15, 4, v14
	s_addc_u32 s15, s15, s87
	v_and_b32_e32 v148, 0xf0, v15
	v_add_u32_e32 v6, s2, v2
	v_lshl_add_u64 v[0:1], s[14:15], 0, v[148:149]
	s_mov_b64 s[14:15], 0x40000
	v_ashrrev_i32_e32 v7, 31, v6
	v_lshl_add_u64 v[4:5], v[0:1], 0, s[14:15]
	v_lshlrev_b64 v[0:1], 11, v[6:7]
	v_lshl_add_u64 v[0:1], v[4:5], 0, v[0:1]
	s_barrier
	v_mad_u64_u32 v[12:13], s[14:15], v2, s93, v[148:149]
	global_load_dwordx4 v[104:107], v[0:1], off
	v_and_b32_e32 v21, 48, v15
	v_ashrrev_i32_e32 v20, 2, v14
	s_lshl_b32 s26, s2, 1
	v_lshlrev_b32_e32 v148, 1, v21
	v_add_u32_e32 v0, 16, v6
	v_ashrrev_i32_e32 v1, 31, v0
	v_lshlrev_b64 v[0:1], 11, v[0:1]
	v_lshl_add_u64 v[0:1], v[4:5], 0, v[0:1]
	global_load_dwordx4 v[108:111], v[0:1], off
	v_add_u32_e32 v0, 32, v6
	v_ashrrev_i32_e32 v1, 31, v0
	v_lshlrev_b64 v[0:1], 11, v[0:1]
	v_lshl_add_u64 v[0:1], v[4:5], 0, v[0:1]
	global_load_dwordx4 v[112:115], v[0:1], off
	v_add_u32_e32 v0, 48, v6
	v_ashrrev_i32_e32 v1, 31, v0
	v_lshlrev_b64 v[0:1], 11, v[0:1]
	v_lshl_add_u64 v[0:1], v[4:5], 0, v[0:1]
	global_load_dwordx4 v[116:119], v[0:1], off
	v_add_u32_e32 v7, 0x1040, v12
	s_waitcnt vmcnt(3)
	ds_write2_b32 v12, v104, v105 offset1:1
	ds_write2_b32 v12, v106, v107 offset0:2 offset1:3
	s_waitcnt vmcnt(2)
	ds_write2_b32 v7, v108, v109 offset1:1
	v_add_u32_e32 v0, 0x1048, v12
	ds_write2_b32 v0, v110, v111 offset1:1
	v_add_u32_e32 v7, 0x2080, v12
	s_waitcnt vmcnt(1)
	ds_write2_b32 v7, v112, v113 offset1:1
	v_add_u32_e32 v0, 0x2088, v12
	ds_write2_b32 v0, v114, v115 offset1:1
	v_add_u32_e32 v4, 0x30c0, v12
	s_waitcnt vmcnt(0)
	ds_write2_b32 v4, v116, v117 offset1:1
	v_add_u32_e32 v0, 0x30c8, v12
	ds_write2_b32 v0, v118, v119 offset1:1
	v_and_b32_e32 v0, -4, v14
	v_mul_u32_u24_e32 v1, 0x41, v21
	v_lshl_add_u32 v2, v1, 2, v0
	s_waitcnt lgkmcnt(0)
	s_barrier
	ds_read2_b32 v[4:5], v2 offset1:65
	v_add_u32_e32 v3, 0x800, v2
	ds_read2_b32 v[12:13], v3 offset0:8 offset1:73
	ds_read2_b32 v[0:1], v2 offset0:130 offset1:195
	ds_read2_b32 v[14:15], v3 offset0:138 offset1:203
	v_add_u32_e32 v3, 0x400, v2
	ds_read2_b32 v[6:7], v3 offset0:4 offset1:69
	v_add_u32_e32 v18, 0xc00, v2
	s_waitcnt lgkmcnt(2)
	v_cvt_pk_bf16_f32 v1, v0, v1
	v_cvt_pk_bf16_f32 v0, v4, v5
	v_cvt_pk_bf16_f32 v4, v12, v13
	v_add_u32_e32 v12, s20, v20
	ds_read2_b32 v[16:17], v18 offset0:12 offset1:77
	ds_read2_b32 v[2:3], v3 offset0:134 offset1:199
	ds_read2_b32 v[18:19], v18 offset0:142 offset1:207
	v_ashrrev_i32_e32 v13, 31, v12
	v_lshlrev_b64 v[12:13], 8, v[12:13]
	v_lshl_add_u64 v[12:13], s[10:11], 0, v[12:13]
	v_lshl_add_u64 v[12:13], v[12:13], 0, s[26:27]
	s_waitcnt lgkmcnt(1)
	v_cvt_pk_bf16_f32 v3, v2, v3
	v_cvt_pk_bf16_f32 v2, v6, v7
	v_lshl_add_u64 v[12:13], v[12:13], 0, v[148:149]
	s_waitcnt lgkmcnt(0)
	v_cvt_pk_bf16_f32 v7, v18, v19
	v_cvt_pk_bf16_f32 v6, v16, v17
	v_cvt_pk_bf16_f32 v5, v14, v15
	global_store_dwordx4 v[12:13], v[0:3], off
	global_store_dwordx4 v[12:13], v[4:7], off offset:16

.LBB0_65:
	s_andn2_b64 vcc, exec, s[14:15]
	s_cbranch_vccnz .LBB0_67
	s_load_dwordx2 s[20:21], s[4:5], 0xa0
	s_add_i32 s2, s84, 0xffffeed0
	s_lshr_b32 s14, s2, 3
	s_add_i32 s26, s14, 2
	s_lshl_b64 s[86:87], s[26:27], 17
	s_waitcnt lgkmcnt(0)
	s_add_u32 s25, s20, s86
	s_mov_b32 s15, s27
	s_addc_u32 s26, s21, s87
	s_lshl_b64 s[14:15], s[14:15], 16
	s_add_u32 s20, s16, s14
	s_addc_u32 s21, s17, s15
	s_and_b32 s2, s45, 0x1c0
	v_mov_b32_e32 v12, v254
	s_lshl_b32 s14, s2, 2
	s_add_u32 s14, s25, s14
	v_ashrrev_i32_e32 v0, 4, v12
	v_lshlrev_b32_e32 v13, 4, v12
	s_addc_u32 s15, s26, 0
	v_and_b32_e32 v148, 0xf0, v13
	v_ashrrev_i32_e32 v1, 31, v0
	v_lshl_add_u64 v[2:3], s[14:15], 0, v[148:149]
	v_lshlrev_b64 v[4:5], 11, v[0:1]
	v_lshl_add_u64 v[4:5], v[2:3], 0, v[4:5]
	s_barrier
	v_mad_u64_u32 v[6:7], s[14:15], v0, s93, v[148:149]
	global_load_dwordx4 v[104:107], v[4:5], off
	s_mov_b32 s14, 0x8000
	v_and_b32_e32 v21, 48, v13
	v_ashrrev_i32_e32 v20, 2, v12
	v_lshlrev_b32_e32 v148, 1, v21
	v_add_co_u32_e32 v0, vcc, s14, v4
	s_mov_b32 s14, 0x10000
	s_nop 0
	v_addc_co_u32_e32 v1, vcc, 0, v5, vcc
	global_load_dwordx4 v[108:111], v[0:1], off
	v_add_co_u32_e32 v0, vcc, s14, v4
	s_nop 0
	v_addc_co_u32_e32 v1, vcc, 0, v5, vcc
	global_load_dwordx4 v[112:115], v[0:1], off
	s_mov_b32 s14, 0x18000
	v_add_co_u32_e32 v0, vcc, s14, v4
	s_nop 0
	v_addc_co_u32_e32 v1, vcc, 0, v5, vcc
	global_load_dwordx4 v[116:119], v[0:1], off
	v_add_u32_e32 v7, 0x1040, v6
	s_waitcnt vmcnt(3)
	ds_write2_b32 v6, v104, v105 offset1:1
	ds_write2_b32 v6, v106, v107 offset0:2 offset1:3
	s_waitcnt vmcnt(2)
	ds_write2_b32 v7, v108, v109 offset1:1
	v_add_u32_e32 v0, 0x1048, v6
	ds_write2_b32 v0, v110, v111 offset1:1
	v_add_u32_e32 v7, 0x2080, v6
	s_waitcnt vmcnt(1)
	ds_write2_b32 v7, v112, v113 offset1:1
	v_add_u32_e32 v0, 0x2088, v6
	ds_write2_b32 v0, v114, v115 offset1:1
	v_add_u32_e32 v7, 0x30c0, v6
	s_waitcnt vmcnt(0)
	ds_write2_b32 v7, v116, v117 offset1:1
	v_add_u32_e32 v0, 0x30c8, v6
	ds_write2_b32 v0, v118, v119 offset1:1
	v_and_b32_e32 v0, -4, v12
	v_mul_u32_u24_e32 v1, 0x41, v21
	v_lshl_add_u32 v2, v1, 2, v0
	s_waitcnt lgkmcnt(0)
	s_barrier
	ds_read2_b32 v[4:5], v2 offset1:65
	v_add_u32_e32 v3, 0x800, v2
	ds_read2_b32 v[12:13], v3 offset0:8 offset1:73
	ds_read2_b32 v[0:1], v2 offset0:130 offset1:195
	ds_read2_b32 v[14:15], v3 offset0:138 offset1:203
	v_add_u32_e32 v3, 0x400, v2
	ds_read2_b32 v[6:7], v3 offset0:4 offset1:69
	v_add_u32_e32 v18, 0xc00, v2
	ds_read2_b32 v[16:17], v18 offset0:12 offset1:77
	ds_read2_b32 v[2:3], v3 offset0:134 offset1:199
	ds_read2_b32 v[18:19], v18 offset0:142 offset1:207
	s_waitcnt lgkmcnt(5)
	v_cvt_pk_bf16_f32 v1, v0, v1
	v_cvt_pk_bf16_f32 v0, v4, v5
	v_cvt_pk_bf16_f32 v4, v12, v13
	v_add_u32_e32 v12, s2, v20
	v_ashrrev_i32_e32 v13, 31, v12
	v_lshlrev_b64 v[12:13], 7, v[12:13]
	v_lshl_add_u64 v[12:13], s[20:21], 0, v[12:13]
	s_waitcnt lgkmcnt(1)
	v_cvt_pk_bf16_f32 v3, v2, v3
	v_cvt_pk_bf16_f32 v2, v6, v7
	v_lshl_add_u64 v[12:13], v[12:13], 0, v[148:149]
	s_waitcnt lgkmcnt(0)
	v_cvt_pk_bf16_f32 v7, v18, v19
	v_cvt_pk_bf16_f32 v6, v16, v17
	v_cvt_pk_bf16_f32 v5, v14, v15
	global_store_dwordx4 v[12:13], v[0:3], off
	global_store_dwordx4 v[12:13], v[4:7], off offset:16

.LBB0_68:
	s_andn2_b64 vcc, exec, s[14:15]
	s_cbranch_vccnz .LBB0_70
	s_load_dwordx2 s[20:21], s[4:5], 0x90
	s_add_i32 s2, s84, 0xffffeee0
	s_lshr_b32 s14, s2, 3
	s_add_i32 s26, s14, 2
	s_lshl_b64 s[86:87], s[26:27], 17
	s_waitcnt lgkmcnt(0)
	s_add_u32 s25, s20, s86
	s_mov_b32 s15, s27
	s_addc_u32 s26, s21, s87
	s_lshl_b64 s[14:15], s[14:15], 16
	s_add_u32 s20, s22, s14
	s_addc_u32 s21, s23, s15
	s_and_b32 s2, s45, 0x1c0
	v_mov_b32_e32 v12, v254
	s_lshl_b32 s14, s2, 2
	s_add_u32 s14, s25, s14
	v_ashrrev_i32_e32 v0, 4, v12
	v_lshlrev_b32_e32 v13, 4, v12
	s_addc_u32 s15, s26, 0
	v_and_b32_e32 v148, 0xf0, v13
	v_ashrrev_i32_e32 v1, 31, v0
	v_lshl_add_u64 v[2:3], s[14:15], 0, v[148:149]
	v_lshlrev_b64 v[4:5], 11, v[0:1]
	v_lshl_add_u64 v[4:5], v[2:3], 0, v[4:5]
	s_barrier
	v_mad_u64_u32 v[6:7], s[14:15], v0, s93, v[148:149]
	global_load_dwordx4 v[104:107], v[4:5], off
	s_mov_b32 s14, 0x8000
	v_and_b32_e32 v21, 48, v13
	v_ashrrev_i32_e32 v20, 2, v12
	v_lshlrev_b32_e32 v148, 1, v21
	v_add_co_u32_e32 v0, vcc, s14, v4
	s_mov_b32 s14, 0x10000
	s_nop 0
	v_addc_co_u32_e32 v1, vcc, 0, v5, vcc
	global_load_dwordx4 v[108:111], v[0:1], off
	v_add_co_u32_e32 v0, vcc, s14, v4
	s_nop 0
	v_addc_co_u32_e32 v1, vcc, 0, v5, vcc
	global_load_dwordx4 v[112:115], v[0:1], off
	s_mov_b32 s14, 0x18000
	v_add_co_u32_e32 v0, vcc, s14, v4
	s_nop 0
	v_addc_co_u32_e32 v1, vcc, 0, v5, vcc
	global_load_dwordx4 v[116:119], v[0:1], off
	v_add_u32_e32 v7, 0x1040, v6
	s_waitcnt vmcnt(3)
	ds_write2_b32 v6, v104, v105 offset1:1
	ds_write2_b32 v6, v106, v107 offset0:2 offset1:3
	s_waitcnt vmcnt(2)
	ds_write2_b32 v7, v108, v109 offset1:1
	v_add_u32_e32 v0, 0x1048, v6
	ds_write2_b32 v0, v110, v111 offset1:1
	v_add_u32_e32 v7, 0x2080, v6
	s_waitcnt vmcnt(1)
	ds_write2_b32 v7, v112, v113 offset1:1
	v_add_u32_e32 v0, 0x2088, v6
	ds_write2_b32 v0, v114, v115 offset1:1
	v_add_u32_e32 v7, 0x30c0, v6
	s_waitcnt vmcnt(0)
	ds_write2_b32 v7, v116, v117 offset1:1
	v_add_u32_e32 v0, 0x30c8, v6
	ds_write2_b32 v0, v118, v119 offset1:1
	v_and_b32_e32 v0, -4, v12
	v_mul_u32_u24_e32 v1, 0x41, v21
	v_lshl_add_u32 v2, v1, 2, v0
	s_waitcnt lgkmcnt(0)
	s_barrier
	ds_read2_b32 v[4:5], v2 offset1:65
	v_add_u32_e32 v3, 0x800, v2
	ds_read2_b32 v[12:13], v3 offset0:8 offset1:73
	ds_read2_b32 v[0:1], v2 offset0:130 offset1:195
	ds_read2_b32 v[14:15], v3 offset0:138 offset1:203
	v_add_u32_e32 v3, 0x400, v2
	ds_read2_b32 v[6:7], v3 offset0:4 offset1:69
	v_add_u32_e32 v18, 0xc00, v2
	ds_read2_b32 v[16:17], v18 offset0:12 offset1:77
	ds_read2_b32 v[2:3], v3 offset0:134 offset1:199
	ds_read2_b32 v[18:19], v18 offset0:142 offset1:207
	s_waitcnt lgkmcnt(5)
	v_cvt_pk_bf16_f32 v1, v0, v1
	v_cvt_pk_bf16_f32 v0, v4, v5
	v_cvt_pk_bf16_f32 v4, v12, v13
	v_add_u32_e32 v12, s2, v20
	v_ashrrev_i32_e32 v13, 31, v12
	v_lshlrev_b64 v[12:13], 7, v[12:13]
	v_lshl_add_u64 v[12:13], s[20:21], 0, v[12:13]
	s_waitcnt lgkmcnt(1)
	v_cvt_pk_bf16_f32 v3, v2, v3
	v_cvt_pk_bf16_f32 v2, v6, v7
	v_lshl_add_u64 v[12:13], v[12:13], 0, v[148:149]
	s_waitcnt lgkmcnt(0)
	v_cvt_pk_bf16_f32 v7, v18, v19
	v_cvt_pk_bf16_f32 v6, v16, v17
	v_cvt_pk_bf16_f32 v5, v14, v15
	global_store_dwordx4 v[12:13], v[0:3], off
	global_store_dwordx4 v[12:13], v[4:7], off offset:16

.LBB0_71:
	s_andn2_b64 vcc, exec, s[14:15]
	s_cbranch_vccnz .LBB0_73
	s_load_dwordx2 s[20:21], s[4:5], 0x100
	s_and_b32 s14, s45, 0x3c0
	s_and_b32 s2, s44, 0x3ffc0
	v_mov_b32_e32 v14, v254
	s_lshl_b32 s15, s14, 2
	s_waitcnt lgkmcnt(0)
	s_add_u32 s20, s20, s15
	v_ashrrev_i32_e32 v2, 4, v14
	v_lshlrev_b32_e32 v15, 4, v14
	s_addc_u32 s21, s21, 0
	v_and_b32_e32 v148, 0xf0, v15
	v_add_u32_e32 v6, s2, v2
	v_lshl_add_u64 v[0:1], s[20:21], 0, v[148:149]
	s_mov_b64 s[20:21], 0x1000000
	v_ashrrev_i32_e32 v7, 31, v6
	v_lshl_add_u64 v[4:5], v[0:1], 0, s[20:21]
	v_lshlrev_b64 v[0:1], 12, v[6:7]
	v_lshl_add_u64 v[0:1], v[4:5], 0, v[0:1]
	s_barrier
	v_mad_u64_u32 v[12:13], s[20:21], v2, s93, v[148:149]
	global_load_dwordx4 v[104:107], v[0:1], off
	v_and_b32_e32 v21, 48, v15
	v_ashrrev_i32_e32 v20, 2, v14
	s_lshl_b32 s26, s2, 1
	v_lshlrev_b32_e32 v148, 1, v21
	v_add_u32_e32 v0, 16, v6
	v_ashrrev_i32_e32 v1, 31, v0
	v_lshlrev_b64 v[0:1], 12, v[0:1]
	v_lshl_add_u64 v[0:1], v[4:5], 0, v[0:1]
	global_load_dwordx4 v[108:111], v[0:1], off
	v_add_u32_e32 v0, 32, v6
	v_ashrrev_i32_e32 v1, 31, v0
	v_lshlrev_b64 v[0:1], 12, v[0:1]
	v_lshl_add_u64 v[0:1], v[4:5], 0, v[0:1]
	global_load_dwordx4 v[112:115], v[0:1], off
	v_add_u32_e32 v0, 48, v6
	v_ashrrev_i32_e32 v1, 31, v0
	v_lshlrev_b64 v[0:1], 12, v[0:1]
	v_lshl_add_u64 v[0:1], v[4:5], 0, v[0:1]
	global_load_dwordx4 v[116:119], v[0:1], off
	v_add_u32_e32 v7, 0x1040, v12
	s_waitcnt vmcnt(3)
	ds_write2_b32 v12, v104, v105 offset1:1
	ds_write2_b32 v12, v106, v107 offset0:2 offset1:3
	s_waitcnt vmcnt(2)
	ds_write2_b32 v7, v108, v109 offset1:1
	v_add_u32_e32 v0, 0x1048, v12
	ds_write2_b32 v0, v110, v111 offset1:1
	v_add_u32_e32 v7, 0x2080, v12
	s_waitcnt vmcnt(1)
	ds_write2_b32 v7, v112, v113 offset1:1
	v_add_u32_e32 v0, 0x2088, v12
	ds_write2_b32 v0, v114, v115 offset1:1
	v_add_u32_e32 v4, 0x30c0, v12
	s_waitcnt vmcnt(0)
	ds_write2_b32 v4, v116, v117 offset1:1
	v_add_u32_e32 v0, 0x30c8, v12
	ds_write2_b32 v0, v118, v119 offset1:1
	v_and_b32_e32 v0, -4, v14
	v_mul_u32_u24_e32 v1, 0x41, v21
	v_lshl_add_u32 v2, v1, 2, v0
	s_waitcnt lgkmcnt(0)
	s_barrier
	ds_read2_b32 v[4:5], v2 offset1:65
	v_add_u32_e32 v3, 0x800, v2
	ds_read2_b32 v[12:13], v3 offset0:8 offset1:73
	ds_read2_b32 v[0:1], v2 offset0:130 offset1:195
	ds_read2_b32 v[14:15], v3 offset0:138 offset1:203
	v_add_u32_e32 v3, 0x400, v2
	ds_read2_b32 v[6:7], v3 offset0:4 offset1:69
	v_add_u32_e32 v18, 0xc00, v2
	s_waitcnt lgkmcnt(2)
	v_cvt_pk_bf16_f32 v1, v0, v1
	v_cvt_pk_bf16_f32 v0, v4, v5
	v_cvt_pk_bf16_f32 v4, v12, v13
	v_add_u32_e32 v12, s14, v20
	ds_read2_b32 v[16:17], v18 offset0:12 offset1:77
	ds_read2_b32 v[2:3], v3 offset0:134 offset1:199
	ds_read2_b32 v[18:19], v18 offset0:142 offset1:207
	v_ashrrev_i32_e32 v13, 31, v12
	v_lshlrev_b64 v[12:13], 13, v[12:13]
	v_lshl_add_u64 v[12:13], s[12:13], 0, v[12:13]
	v_lshl_add_u64 v[12:13], v[12:13], 0, s[26:27]
	s_waitcnt lgkmcnt(1)
	v_cvt_pk_bf16_f32 v3, v2, v3
	v_cvt_pk_bf16_f32 v2, v6, v7
	v_lshl_add_u64 v[12:13], v[12:13], 0, v[148:149]
	s_waitcnt lgkmcnt(0)
	v_cvt_pk_bf16_f32 v7, v18, v19
	v_cvt_pk_bf16_f32 v6, v16, v17
	v_cvt_pk_bf16_f32 v5, v14, v15
	global_store_dwordx4 v[12:13], v[0:3], off
	global_store_dwordx4 v[12:13], v[4:7], off offset:16

.LBB0_74:
	s_andn2_b64 vcc, exec, s[14:15]
	s_cbranch_vccnz .LBB0_76
	s_load_dwordx2 s[20:21], s[4:5], 0xf8
	s_add_i32 s14, s45, 0xfffdb800
	s_add_i32 s2, s84, 0xfffff6e0
	s_and_b32 s14, s14, 0xfc0
	s_and_b32 s2, s2, 0xffc0
	v_mov_b32_e32 v14, v254
	s_lshl_b32 s15, s14, 2
	s_waitcnt lgkmcnt(0)
	s_add_u32 s20, s20, s15
	v_ashrrev_i32_e32 v2, 4, v14
	v_lshlrev_b32_e32 v15, 4, v14
	s_addc_u32 s21, s21, 0
	v_and_b32_e32 v148, 0xf0, v15
	v_add_u32_e32 v6, s2, v2
	v_lshl_add_u64 v[0:1], s[20:21], 0, v[148:149]
	s_mov_b64 s[20:21], 0x1000000
	v_ashrrev_i32_e32 v7, 31, v6
	v_lshl_add_u64 v[4:5], v[0:1], 0, s[20:21]
	v_lshlrev_b64 v[0:1], 14, v[6:7]
	v_lshl_add_u64 v[0:1], v[4:5], 0, v[0:1]
	s_barrier
	v_mad_u64_u32 v[12:13], s[20:21], v2, s93, v[148:149]
	global_load_dwordx4 v[104:107], v[0:1], off
	v_and_b32_e32 v21, 48, v15
	v_ashrrev_i32_e32 v20, 2, v14
	s_lshl_b32 s26, s2, 1
	v_lshlrev_b32_e32 v148, 1, v21
	v_add_u32_e32 v0, 16, v6
	v_ashrrev_i32_e32 v1, 31, v0
	v_lshlrev_b64 v[0:1], 14, v[0:1]
	v_lshl_add_u64 v[0:1], v[4:5], 0, v[0:1]
	global_load_dwordx4 v[108:111], v[0:1], off
	v_add_u32_e32 v0, 32, v6
	v_ashrrev_i32_e32 v1, 31, v0
	v_lshlrev_b64 v[0:1], 14, v[0:1]
	v_lshl_add_u64 v[0:1], v[4:5], 0, v[0:1]
	global_load_dwordx4 v[112:115], v[0:1], off
	v_add_u32_e32 v0, 48, v6
	v_ashrrev_i32_e32 v1, 31, v0
	v_lshlrev_b64 v[0:1], 14, v[0:1]
	v_lshl_add_u64 v[0:1], v[4:5], 0, v[0:1]
	global_load_dwordx4 v[116:119], v[0:1], off
	v_add_u32_e32 v7, 0x1040, v12
	s_waitcnt vmcnt(3)
	ds_write2_b32 v12, v104, v105 offset1:1
	ds_write2_b32 v12, v106, v107 offset0:2 offset1:3
	s_waitcnt vmcnt(2)
	ds_write2_b32 v7, v108, v109 offset1:1
	v_add_u32_e32 v0, 0x1048, v12
	ds_write2_b32 v0, v110, v111 offset1:1
	v_add_u32_e32 v7, 0x2080, v12
	s_waitcnt vmcnt(1)
	ds_write2_b32 v7, v112, v113 offset1:1
	v_add_u32_e32 v0, 0x2088, v12
	ds_write2_b32 v0, v114, v115 offset1:1
	v_add_u32_e32 v4, 0x30c0, v12
	s_waitcnt vmcnt(0)
	ds_write2_b32 v4, v116, v117 offset1:1
	v_add_u32_e32 v0, 0x30c8, v12
	ds_write2_b32 v0, v118, v119 offset1:1
	v_and_b32_e32 v0, -4, v14
	v_mul_u32_u24_e32 v1, 0x41, v21
	v_lshl_add_u32 v2, v1, 2, v0
	s_waitcnt lgkmcnt(0)
	s_barrier
	ds_read2_b32 v[4:5], v2 offset1:65
	v_add_u32_e32 v3, 0x800, v2
	ds_read2_b32 v[12:13], v3 offset0:8 offset1:73
	ds_read2_b32 v[0:1], v2 offset0:130 offset1:195
	ds_read2_b32 v[14:15], v3 offset0:138 offset1:203
	v_add_u32_e32 v3, 0x400, v2
	ds_read2_b32 v[6:7], v3 offset0:4 offset1:69
	v_add_u32_e32 v18, 0xc00, v2
	s_waitcnt lgkmcnt(2)
	v_cvt_pk_bf16_f32 v1, v0, v1
	v_cvt_pk_bf16_f32 v0, v4, v5
	v_cvt_pk_bf16_f32 v4, v12, v13
	v_add_u32_e32 v12, s14, v20
	ds_read2_b32 v[16:17], v18 offset0:12 offset1:77
	ds_read2_b32 v[2:3], v3 offset0:134 offset1:199
	ds_read2_b32 v[18:19], v18 offset0:142 offset1:207
	v_ashrrev_i32_e32 v13, 31, v12
	v_lshlrev_b64 v[12:13], 11, v[12:13]
	v_lshl_add_u64 v[12:13], s[8:9], 0, v[12:13]
	v_lshl_add_u64 v[12:13], v[12:13], 0, s[26:27]
	s_waitcnt lgkmcnt(1)
	v_cvt_pk_bf16_f32 v3, v2, v3
	v_cvt_pk_bf16_f32 v2, v6, v7
	v_lshl_add_u64 v[12:13], v[12:13], 0, v[148:149]
	s_waitcnt lgkmcnt(0)
	v_cvt_pk_bf16_f32 v7, v18, v19
	v_cvt_pk_bf16_f32 v6, v16, v17
	v_cvt_pk_bf16_f32 v5, v14, v15
	global_store_dwordx4 v[12:13], v[0:3], off
	global_store_dwordx4 v[12:13], v[4:7], off offset:16

.LBB0_77:
	s_andn2_b64 vcc, exec, s[14:15]
	s_cbranch_vccnz .LBB0_79
	s_load_dwordx2 s[20:21], s[4:5], 0xe0
	s_add_i32 s2, s44, 0xfffc3800
	s_and_b32 s14, s45, 0x3c0
	s_and_b32 s2, s2, 0x3c0
	v_mov_b32_e32 v14, v254
	s_lshl_b32 s15, s14, 2
	s_waitcnt lgkmcnt(0)
	s_add_u32 s20, s20, s15
	v_ashrrev_i32_e32 v2, 4, v14
	v_lshlrev_b32_e32 v15, 4, v14
	s_addc_u32 s21, s21, 0
	v_and_b32_e32 v148, 0xf0, v15
	v_add_u32_e32 v6, s2, v2
	v_lshl_add_u64 v[0:1], s[20:21], 0, v[148:149]
	s_mov_b64 s[20:21], 0x400000
	v_ashrrev_i32_e32 v7, 31, v6
	v_lshl_add_u64 v[4:5], v[0:1], 0, s[20:21]
	v_lshlrev_b64 v[0:1], 12, v[6:7]
	v_lshl_add_u64 v[0:1], v[4:5], 0, v[0:1]
	s_barrier
	v_mad_u64_u32 v[12:13], s[20:21], v2, s93, v[148:149]
	global_load_dwordx4 v[104:107], v[0:1], off
	v_and_b32_e32 v21, 48, v15
	v_ashrrev_i32_e32 v20, 2, v14
	s_lshl_b32 s26, s2, 1
	v_lshlrev_b32_e32 v148, 1, v21
	v_add_u32_e32 v0, 16, v6
	v_ashrrev_i32_e32 v1, 31, v0
	v_lshlrev_b64 v[0:1], 12, v[0:1]
	v_lshl_add_u64 v[0:1], v[4:5], 0, v[0:1]
	global_load_dwordx4 v[108:111], v[0:1], off
	v_add_u32_e32 v0, 32, v6
	v_ashrrev_i32_e32 v1, 31, v0
	v_lshlrev_b64 v[0:1], 12, v[0:1]
	v_lshl_add_u64 v[0:1], v[4:5], 0, v[0:1]
	global_load_dwordx4 v[112:115], v[0:1], off
	v_add_u32_e32 v0, 48, v6
	v_ashrrev_i32_e32 v1, 31, v0
	v_lshlrev_b64 v[0:1], 12, v[0:1]
	v_lshl_add_u64 v[0:1], v[4:5], 0, v[0:1]
	global_load_dwordx4 v[116:119], v[0:1], off
	v_add_u32_e32 v7, 0x1040, v12
	s_waitcnt vmcnt(3)
	ds_write2_b32 v12, v104, v105 offset1:1
	ds_write2_b32 v12, v106, v107 offset0:2 offset1:3
	s_waitcnt vmcnt(2)
	ds_write2_b32 v7, v108, v109 offset1:1
	v_add_u32_e32 v0, 0x1048, v12
	ds_write2_b32 v0, v110, v111 offset1:1
	v_add_u32_e32 v7, 0x2080, v12
	s_waitcnt vmcnt(1)
	ds_write2_b32 v7, v112, v113 offset1:1
	v_add_u32_e32 v0, 0x2088, v12
	ds_write2_b32 v0, v114, v115 offset1:1
	v_add_u32_e32 v4, 0x30c0, v12
	s_waitcnt vmcnt(0)
	ds_write2_b32 v4, v116, v117 offset1:1
	v_add_u32_e32 v0, 0x30c8, v12
	ds_write2_b32 v0, v118, v119 offset1:1
	v_and_b32_e32 v0, -4, v14
	v_mul_u32_u24_e32 v1, 0x41, v21
	v_lshl_add_u32 v2, v1, 2, v0
	s_waitcnt lgkmcnt(0)
	s_barrier
	ds_read2_b32 v[4:5], v2 offset1:65
	v_add_u32_e32 v3, 0x800, v2
	ds_read2_b32 v[12:13], v3 offset0:8 offset1:73
	ds_read2_b32 v[0:1], v2 offset0:130 offset1:195
	ds_read2_b32 v[14:15], v3 offset0:138 offset1:203
	v_add_u32_e32 v3, 0x400, v2
	ds_read2_b32 v[6:7], v3 offset0:4 offset1:69
	v_add_u32_e32 v18, 0xc00, v2
	s_waitcnt lgkmcnt(2)
	v_cvt_pk_bf16_f32 v1, v0, v1
	v_cvt_pk_bf16_f32 v0, v4, v5
	v_cvt_pk_bf16_f32 v4, v12, v13
	v_add_u32_e32 v12, s14, v20
	ds_read2_b32 v[16:17], v18 offset0:12 offset1:77
	ds_read2_b32 v[2:3], v3 offset0:134 offset1:199
	ds_read2_b32 v[18:19], v18 offset0:142 offset1:207
	v_ashrrev_i32_e32 v13, 31, v12
	v_lshlrev_b64 v[12:13], 11, v[12:13]
	v_lshl_add_u64 v[12:13], s[28:29], 0, v[12:13]
	v_lshl_add_u64 v[12:13], v[12:13], 0, s[26:27]
	s_waitcnt lgkmcnt(1)
	v_cvt_pk_bf16_f32 v3, v2, v3
	v_cvt_pk_bf16_f32 v2, v6, v7
	v_lshl_add_u64 v[12:13], v[12:13], 0, v[148:149]
	s_waitcnt lgkmcnt(0)
	v_cvt_pk_bf16_f32 v7, v18, v19
	v_cvt_pk_bf16_f32 v6, v16, v17
	v_cvt_pk_bf16_f32 v5, v14, v15
	global_store_dwordx4 v[12:13], v[0:3], off
	global_store_dwordx4 v[12:13], v[4:7], off offset:16

.LBB0_80:
	s_andn2_b64 vcc, exec, s[14:15]
	s_cbranch_vccnz .LBB0_82
	s_load_dwordx2 s[20:21], s[4:5], 0xd8
	s_add_i32 s2, s84, 0xfffff960
	s_lshr_b32 s14, s2, 7
	s_add_i32 s26, s14, 3
	s_lshl_b64 s[86:87], s[26:27], 21
	s_waitcnt lgkmcnt(0)
	s_add_u32 s25, s20, s86
	s_mov_b32 s15, s27
	s_addc_u32 s26, s21, s87
	s_lshl_b64 s[14:15], s[14:15], 20
	s_add_u32 s20, s36, s14
	s_addc_u32 s21, s37, s15
	s_add_i32 s2, s44, 0xfffc1a00
	s_and_b32 s14, s45, 0x3c0
	v_mov_b32_e32 v14, v254
	s_and_b32 s2, s2, 0x1c0
	s_lshl_b32 s15, s14, 2
	v_ashrrev_i32_e32 v2, 4, v14
	s_add_u32 s86, s25, s15
	v_lshlrev_b32_e32 v15, 4, v14
	v_add_u32_e32 v6, s2, v2
	s_addc_u32 s87, s26, 0
	v_and_b32_e32 v148, 0xf0, v15
	v_ashrrev_i32_e32 v7, 31, v6
	v_lshl_add_u64 v[4:5], s[86:87], 0, v[148:149]
	v_lshlrev_b64 v[0:1], 12, v[6:7]
	v_lshl_add_u64 v[0:1], v[4:5], 0, v[0:1]
	s_barrier
	v_mad_u64_u32 v[12:13], s[86:87], v2, s93, v[148:149]
	global_load_dwordx4 v[104:107], v[0:1], off
	v_and_b32_e32 v21, 48, v15
	v_ashrrev_i32_e32 v20, 2, v14
	s_lshl_b32 s26, s2, 1
	v_lshlrev_b32_e32 v148, 1, v21
	v_add_u32_e32 v0, 16, v6
	v_ashrrev_i32_e32 v1, 31, v0
	v_lshlrev_b64 v[0:1], 12, v[0:1]
	v_lshl_add_u64 v[0:1], v[4:5], 0, v[0:1]
	global_load_dwordx4 v[108:111], v[0:1], off
	v_add_u32_e32 v0, 32, v6
	v_ashrrev_i32_e32 v1, 31, v0
	v_lshlrev_b64 v[0:1], 12, v[0:1]
	v_lshl_add_u64 v[0:1], v[4:5], 0, v[0:1]
	global_load_dwordx4 v[112:115], v[0:1], off
	v_add_u32_e32 v0, 48, v6
	v_ashrrev_i32_e32 v1, 31, v0
	v_lshlrev_b64 v[0:1], 12, v[0:1]
	v_lshl_add_u64 v[0:1], v[4:5], 0, v[0:1]
	global_load_dwordx4 v[116:119], v[0:1], off
	v_add_u32_e32 v7, 0x1040, v12
	s_waitcnt vmcnt(3)
	ds_write2_b32 v12, v104, v105 offset1:1
	ds_write2_b32 v12, v106, v107 offset0:2 offset1:3
	s_waitcnt vmcnt(2)
	ds_write2_b32 v7, v108, v109 offset1:1
	v_add_u32_e32 v0, 0x1048, v12
	ds_write2_b32 v0, v110, v111 offset1:1
	v_add_u32_e32 v7, 0x2080, v12
	s_waitcnt vmcnt(1)
	ds_write2_b32 v7, v112, v113 offset1:1
	v_add_u32_e32 v0, 0x2088, v12
	ds_write2_b32 v0, v114, v115 offset1:1
	v_add_u32_e32 v4, 0x30c0, v12
	s_waitcnt vmcnt(0)
	ds_write2_b32 v4, v116, v117 offset1:1
	v_add_u32_e32 v0, 0x30c8, v12
	ds_write2_b32 v0, v118, v119 offset1:1
	v_and_b32_e32 v0, -4, v14
	v_mul_u32_u24_e32 v1, 0x41, v21
	v_lshl_add_u32 v2, v1, 2, v0
	s_waitcnt lgkmcnt(0)
	s_barrier
	ds_read2_b32 v[4:5], v2 offset1:65
	v_add_u32_e32 v3, 0x800, v2
	ds_read2_b32 v[12:13], v3 offset0:8 offset1:73
	ds_read2_b32 v[0:1], v2 offset0:130 offset1:195
	ds_read2_b32 v[14:15], v3 offset0:138 offset1:203
	v_add_u32_e32 v3, 0x400, v2
	ds_read2_b32 v[6:7], v3 offset0:4 offset1:69
	v_add_u32_e32 v18, 0xc00, v2
	s_waitcnt lgkmcnt(2)
	v_cvt_pk_bf16_f32 v1, v0, v1
	v_cvt_pk_bf16_f32 v0, v4, v5
	v_cvt_pk_bf16_f32 v4, v12, v13
	v_add_u32_e32 v12, s14, v20
	ds_read2_b32 v[16:17], v18 offset0:12 offset1:77
	ds_read2_b32 v[2:3], v3 offset0:134 offset1:199
	ds_read2_b32 v[18:19], v18 offset0:142 offset1:207
	v_ashrrev_i32_e32 v13, 31, v12
	v_lshlrev_b64 v[12:13], 10, v[12:13]
	v_lshl_add_u64 v[12:13], s[20:21], 0, v[12:13]
	v_lshl_add_u64 v[12:13], v[12:13], 0, s[26:27]
	s_waitcnt lgkmcnt(1)
	v_cvt_pk_bf16_f32 v3, v2, v3
	v_cvt_pk_bf16_f32 v2, v6, v7
	v_lshl_add_u64 v[12:13], v[12:13], 0, v[148:149]
	s_waitcnt lgkmcnt(0)
	v_cvt_pk_bf16_f32 v7, v18, v19
	v_cvt_pk_bf16_f32 v6, v16, v17
	v_cvt_pk_bf16_f32 v5, v14, v15
	global_store_dwordx4 v[12:13], v[0:3], off
	global_store_dwordx4 v[12:13], v[4:7], off offset:16

.LBB0_83:
	s_andn2_b64 vcc, exec, s[14:15]
	s_cbranch_vccnz .LBB0_52
	s_mul_hi_i32 s2, s84, 0x4d4873ed
	s_lshr_b32 s20, s2, 31
	s_ashr_i32 s2, s2, 5
	s_load_dwordx2 s[14:15], s[4:5], 0x48
	s_add_i32 s2, s2, s20
	s_mul_i32 s21, s2, 0xffffe580
	s_add_i32 s86, s45, s21
	s_ashr_i32 s87, s86, 31
	s_lshl_b32 s20, s2, 6
	v_mov_b32_e32 v12, v254
	s_lshl_b64 s[86:87], s[86:87], 2
	s_waitcnt lgkmcnt(0)
	s_add_u32 s14, s14, s86
	v_lshlrev_b32_e32 v13, 4, v12
	s_addc_u32 s15, s15, s87
	v_and_b32_e32 v148, 0xf0, v13
	v_ashrrev_i32_e32 v2, 4, v12
	v_lshl_add_u64 v[0:1], s[14:15], 0, v[148:149]
	s_mov_b64 s[14:15], 0x1a80000
	v_lshl_add_u64 v[4:5], v[0:1], 0, s[14:15]
	v_add_u32_e32 v14, s20, v2
	s_movk_i32 s21, 0x6a00
	v_mad_i64_i32 v[0:1], s[14:15], v14, s21, v[4:5]
	s_barrier
	v_mad_u64_u32 v[6:7], s[14:15], v2, s93, v[148:149]
	global_load_dwordx4 v[104:107], v[0:1], off
	v_and_b32_e32 v21, 48, v13
	v_ashrrev_i32_e32 v20, 2, v12
	s_mulk_i32 s2, 0x1a80
	v_lshlrev_b32_e32 v148, 1, v21
	v_add_u32_e32 v0, 16, v14
	v_mad_i64_i32 v[0:1], s[14:15], v0, s21, v[4:5]
	global_load_dwordx4 v[108:111], v[0:1], off
	v_add_u32_e32 v0, 32, v14
	v_mad_i64_i32 v[0:1], s[14:15], v0, s21, v[4:5]
	global_load_dwordx4 v[112:115], v[0:1], off
	v_add_u32_e32 v0, 48, v14
	v_mad_i64_i32 v[0:1], s[14:15], v0, s21, v[4:5]
	global_load_dwordx4 v[116:119], v[0:1], off
	s_ashr_i32 s21, s20, 31
	v_add_u32_e32 v7, 0x1040, v6
	s_waitcnt vmcnt(3)
	ds_write2_b32 v6, v104, v105 offset1:1
	ds_write2_b32 v6, v106, v107 offset0:2 offset1:3
	s_waitcnt vmcnt(2)
	ds_write2_b32 v7, v108, v109 offset1:1
	v_add_u32_e32 v0, 0x1048, v6
	ds_write2_b32 v0, v110, v111 offset1:1
	v_add_u32_e32 v7, 0x2080, v6
	s_waitcnt vmcnt(1)
	ds_write2_b32 v7, v112, v113 offset1:1
	v_add_u32_e32 v0, 0x2088, v6
	ds_write2_b32 v0, v114, v115 offset1:1
	v_add_u32_e32 v4, 0x30c0, v6
	s_waitcnt vmcnt(0)
	ds_write2_b32 v4, v116, v117 offset1:1
	v_add_u32_e32 v0, 0x30c8, v6
	ds_write2_b32 v0, v118, v119 offset1:1
	v_and_b32_e32 v0, -4, v12
	v_mul_u32_u24_e32 v1, 0x41, v21
	v_lshl_add_u32 v2, v1, 2, v0
	s_waitcnt lgkmcnt(0)
	s_barrier
	ds_read2_b32 v[4:5], v2 offset1:65
	v_add_u32_e32 v3, 0x800, v2
	ds_read2_b32 v[12:13], v3 offset0:8 offset1:73
	ds_read2_b32 v[0:1], v2 offset0:130 offset1:195
	ds_read2_b32 v[14:15], v3 offset0:138 offset1:203
	v_add_u32_e32 v3, 0x400, v2
	ds_read2_b32 v[6:7], v3 offset0:4 offset1:69
	v_add_u32_e32 v18, 0xc00, v2
	s_waitcnt lgkmcnt(2)
	v_cvt_pk_bf16_f32 v1, v0, v1
	v_cvt_pk_bf16_f32 v0, v4, v5
	v_cvt_pk_bf16_f32 v4, v12, v13
	v_subrev_u32_e32 v12, s2, v20
	v_add_u32_e32 v12, s45, v12
	ds_read2_b32 v[16:17], v18 offset0:12 offset1:77
	ds_read2_b32 v[2:3], v3 offset0:134 offset1:199
	ds_read2_b32 v[18:19], v18 offset0:142 offset1:207
	v_ashrrev_i32_e32 v13, 31, v12
	v_lshlrev_b64 v[12:13], 11, v[12:13]
	v_lshl_add_u64 v[12:13], s[30:31], 0, v[12:13]
	v_lshl_add_u64 v[12:13], s[20:21], 1, v[12:13]
	s_waitcnt lgkmcnt(1)
	v_cvt_pk_bf16_f32 v3, v2, v3
	v_cvt_pk_bf16_f32 v2, v6, v7
	v_lshl_add_u64 v[12:13], v[12:13], 0, v[148:149]
	s_waitcnt lgkmcnt(0)
	v_cvt_pk_bf16_f32 v7, v18, v19
	v_cvt_pk_bf16_f32 v6, v16, v17
	v_cvt_pk_bf16_f32 v5, v14, v15
	global_store_dwordx4 v[12:13], v[0:3], off
	global_store_dwordx4 v[12:13], v[4:7], off offset:16
	s_branch .LBB0_52

.LBB0_635:
	s_andn2_b64 vcc, exec, s[14:15]
	s_cbranch_vccnz .LBB0_637
	s_add_i32 s2, s84, 0xffffeec0
	s_cmp_gt_u32 s2, 7
	s_cselect_b32 s22, 64, 0
	s_add_i32 s16, s84, 0xffffeeb8
	s_load_dwordx2 s[14:15], s[4:5], 0xc0
	s_cmp_lt_u32 s2, 8
	s_cselect_b32 s2, s2, s16
	s_lshl_b32 s20, s2, 6
	v_mov_b32_e32 v15, v254
	s_ashr_i32 s21, s20, 31
	s_lshl_b64 s[16:17], s[20:21], 2
	v_ashrrev_i32_e32 v16, 4, v15
	s_waitcnt lgkmcnt(0)
	s_add_u32 s14, s14, s16
	v_lshlrev_b32_e32 v18, 4, v15
	v_add_u32_e32 v6, s22, v16
	s_addc_u32 s15, s15, s17
	v_and_b32_e32 v0, 0xf0, v18
	v_mov_b32_e32 v1, v149
	v_ashrrev_i32_e32 v7, 31, v6
	v_lshl_add_u64 v[4:5], s[14:15], 0, v[0:1]
	v_lshlrev_b64 v[2:3], 11, v[6:7]
	v_lshl_add_u64 v[2:3], v[4:5], 0, v[2:3]
	s_waitcnt vmcnt(0)
	s_barrier
	v_mad_u64_u32 v[16:17], s[14:15], v16, s93, v[0:1]
	global_load_dwordx4 v[104:107], v[2:3], off
	v_and_b32_e32 v25, 48, v18
	v_ashrrev_i32_e32 v24, 2, v15
	s_lshl_b32 s26, s22, 1
	v_add_u32_e32 v0, 16, v6
	v_ashrrev_i32_e32 v1, 31, v0
	v_lshlrev_b64 v[0:1], 11, v[0:1]
	v_lshl_add_u64 v[0:1], v[4:5], 0, v[0:1]
	global_load_dwordx4 v[108:111], v[0:1], off
	v_add_u32_e32 v0, 32, v6
	v_ashrrev_i32_e32 v1, 31, v0
	v_lshlrev_b64 v[0:1], 11, v[0:1]
	v_lshl_add_u64 v[0:1], v[4:5], 0, v[0:1]
	global_load_dwordx4 v[112:115], v[0:1], off
	v_add_u32_e32 v0, 48, v6
	v_ashrrev_i32_e32 v1, 31, v0
	v_lshlrev_b64 v[0:1], 11, v[0:1]
	v_lshl_add_u64 v[0:1], v[4:5], 0, v[0:1]
	global_load_dwordx4 v[116:119], v[0:1], off
	v_add_u32_e32 v7, 0x1040, v16
	s_waitcnt vmcnt(3)
	ds_write2_b32 v16, v104, v105 offset1:1
	ds_write2_b32 v16, v106, v107 offset0:2 offset1:3
	s_waitcnt vmcnt(2)
	ds_write2_b32 v7, v108, v109 offset1:1
	v_add_u32_e32 v0, 0x1048, v16
	ds_write2_b32 v0, v110, v111 offset1:1
	v_add_u32_e32 v7, 0x2080, v16
	s_waitcnt vmcnt(1)
	ds_write2_b32 v7, v112, v113 offset1:1
	v_add_u32_e32 v0, 0x2088, v16
	ds_write2_b32 v0, v114, v115 offset1:1
	v_add_u32_e32 v4, 0x30c0, v16
	s_waitcnt vmcnt(0)
	ds_write2_b32 v4, v116, v117 offset1:1
	v_add_u32_e32 v0, 0x30c8, v16
	ds_write2_b32 v0, v118, v119 offset1:1
	v_and_b32_e32 v0, -4, v15
	v_mul_u32_u24_e32 v1, 0x41, v25
	v_lshl_add_u32 v2, v1, 2, v0
	s_waitcnt lgkmcnt(0)
	s_barrier
	ds_read2_b32 v[4:5], v2 offset1:65
	v_add_u32_e32 v3, 0x800, v2
	ds_read2_b32 v[16:17], v3 offset0:8 offset1:73
	ds_read2_b32 v[0:1], v2 offset0:130 offset1:195
	ds_read2_b32 v[18:19], v3 offset0:138 offset1:203
	v_add_u32_e32 v3, 0x400, v2
	ds_read2_b32 v[6:7], v3 offset0:4 offset1:69
	v_add_u32_e32 v15, 0xc00, v2
	s_waitcnt lgkmcnt(2)
	v_cvt_pk_bf16_f32 v1, v0, v1
	v_cvt_pk_bf16_f32 v0, v4, v5
	v_cvt_pk_bf16_f32 v4, v16, v17
	v_add_u32_e32 v16, s20, v24
	ds_read2_b32 v[20:21], v15 offset0:12 offset1:77
	ds_read2_b32 v[2:3], v3 offset0:134 offset1:199
	ds_read2_b32 v[22:23], v15 offset0:142 offset1:207
	v_ashrrev_i32_e32 v17, 31, v16
	v_lshlrev_b64 v[16:17], 8, v[16:17]
	v_lshl_add_u64 v[16:17], s[10:11], 0, v[16:17]
	s_waitcnt lgkmcnt(4)
	v_cvt_pk_bf16_f32 v5, v18, v19
	v_lshl_add_u64 v[16:17], v[16:17], 0, s[26:27]
	v_lshlrev_b32_e32 v18, 1, v25
	v_mov_b32_e32 v19, v149
	s_waitcnt lgkmcnt(1)
	v_cvt_pk_bf16_f32 v3, v2, v3
	v_cvt_pk_bf16_f32 v2, v6, v7
	v_lshl_add_u64 v[16:17], v[16:17], 0, v[18:19]
	s_waitcnt lgkmcnt(0)
	v_cvt_pk_bf16_f32 v7, v22, v23
	v_cvt_pk_bf16_f32 v6, v20, v21
	global_store_dwordx4 v[16:17], v[0:3], off
	global_store_dwordx4 v[16:17], v[4:7], off offset:16

.LBB0_638:
	s_andn2_b64 vcc, exec, s[14:15]
	s_cbranch_vccnz .LBB0_640
	s_load_dwordx2 s[14:15], s[4:5], 0xa0
	s_add_i32 s2, s84, 0xffffeed0
	s_lshr_b32 s26, s2, 3
	s_lshl_b64 s[16:17], s[26:27], 17
	v_mov_b32_e32 v15, v254
	s_waitcnt lgkmcnt(0)
	s_add_u32 s2, s14, s16
	s_addc_u32 s16, s15, s17
	s_lshl_b64 s[14:15], s[26:27], 16
	s_add_u32 s20, s40, s14
	s_addc_u32 s21, s41, s15
	s_lshl_b32 s14, s84, 6
	s_and_b32 s17, s14, 0x1c0
	s_lshl_b32 s14, s17, 2
	s_add_u32 s14, s2, s14
	v_ashrrev_i32_e32 v0, 4, v15
	v_lshlrev_b32_e32 v16, 4, v15
	s_addc_u32 s15, s16, 0
	v_and_b32_e32 v2, 0xf0, v16
	v_mov_b32_e32 v3, v149
	v_ashrrev_i32_e32 v1, 31, v0
	v_lshl_add_u64 v[4:5], s[14:15], 0, v[2:3]
	v_lshlrev_b64 v[6:7], 11, v[0:1]
	v_lshl_add_u64 v[4:5], v[4:5], 0, v[6:7]
	s_waitcnt vmcnt(0)
	s_barrier
	v_mad_u64_u32 v[6:7], s[14:15], v0, s93, v[2:3]
	global_load_dwordx4 v[104:107], v[4:5], off
	s_mov_b32 s2, 0x8000
	v_and_b32_e32 v25, 48, v16
	v_ashrrev_i32_e32 v24, 2, v15
	v_add_co_u32_e32 v0, vcc, s2, v4
	s_mov_b32 s2, 0x10000
	s_nop 0
	v_addc_co_u32_e32 v1, vcc, 0, v5, vcc
	global_load_dwordx4 v[108:111], v[0:1], off
	v_add_co_u32_e32 v0, vcc, s2, v4
	s_nop 0
	v_addc_co_u32_e32 v1, vcc, 0, v5, vcc
	global_load_dwordx4 v[112:115], v[0:1], off
	s_mov_b32 s2, 0x18000
	v_add_co_u32_e32 v0, vcc, s2, v4
	s_nop 0
	v_addc_co_u32_e32 v1, vcc, 0, v5, vcc
	global_load_dwordx4 v[116:119], v[0:1], off
	v_add_u32_e32 v7, 0x1040, v6
	s_waitcnt vmcnt(3)
	ds_write2_b32 v6, v104, v105 offset1:1
	ds_write2_b32 v6, v106, v107 offset0:2 offset1:3
	s_waitcnt vmcnt(2)
	ds_write2_b32 v7, v108, v109 offset1:1
	v_add_u32_e32 v0, 0x1048, v6
	ds_write2_b32 v0, v110, v111 offset1:1
	v_add_u32_e32 v7, 0x2080, v6
	s_waitcnt vmcnt(1)
	ds_write2_b32 v7, v112, v113 offset1:1
	v_add_u32_e32 v0, 0x2088, v6
	ds_write2_b32 v0, v114, v115 offset1:1
	v_add_u32_e32 v7, 0x30c0, v6
	s_waitcnt vmcnt(0)
	ds_write2_b32 v7, v116, v117 offset1:1
	v_add_u32_e32 v0, 0x30c8, v6
	ds_write2_b32 v0, v118, v119 offset1:1
	v_and_b32_e32 v0, -4, v15
	v_mul_u32_u24_e32 v1, 0x41, v25
	v_lshl_add_u32 v2, v1, 2, v0
	s_waitcnt lgkmcnt(0)
	s_barrier
	ds_read2_b32 v[4:5], v2 offset1:65
	v_add_u32_e32 v3, 0x800, v2
	ds_read2_b32 v[16:17], v3 offset0:8 offset1:73
	ds_read2_b32 v[0:1], v2 offset0:130 offset1:195
	ds_read2_b32 v[18:19], v3 offset0:138 offset1:203
	v_add_u32_e32 v3, 0x400, v2
	ds_read2_b32 v[6:7], v3 offset0:4 offset1:69
	v_add_u32_e32 v15, 0xc00, v2
	ds_read2_b32 v[20:21], v15 offset0:12 offset1:77
	ds_read2_b32 v[2:3], v3 offset0:134 offset1:199
	ds_read2_b32 v[22:23], v15 offset0:142 offset1:207
	s_waitcnt lgkmcnt(5)
	v_cvt_pk_bf16_f32 v1, v0, v1
	v_cvt_pk_bf16_f32 v0, v4, v5
	v_cvt_pk_bf16_f32 v4, v16, v17
	v_add_u32_e32 v16, s17, v24
	v_ashrrev_i32_e32 v17, 31, v16
	v_lshlrev_b64 v[16:17], 7, v[16:17]
	s_waitcnt lgkmcnt(4)
	v_cvt_pk_bf16_f32 v5, v18, v19
	v_lshl_add_u64 v[16:17], s[20:21], 0, v[16:17]
	v_lshlrev_b32_e32 v18, 1, v25
	v_mov_b32_e32 v19, v149
	s_waitcnt lgkmcnt(1)
	v_cvt_pk_bf16_f32 v3, v2, v3
	v_cvt_pk_bf16_f32 v2, v6, v7
	v_lshl_add_u64 v[16:17], v[16:17], 0, v[18:19]
	s_waitcnt lgkmcnt(0)
	v_cvt_pk_bf16_f32 v7, v22, v23
	v_cvt_pk_bf16_f32 v6, v20, v21
	global_store_dwordx4 v[16:17], v[0:3], off
	global_store_dwordx4 v[16:17], v[4:7], off offset:16

.LBB0_641:
	s_andn2_b64 vcc, exec, s[14:15]
	s_cbranch_vccnz .LBB0_643
	s_load_dwordx2 s[14:15], s[4:5], 0x90
	s_add_i32 s2, s84, 0xffffeee0
	s_lshr_b32 s26, s2, 3
	s_lshl_b64 s[16:17], s[26:27], 17
	v_mov_b32_e32 v15, v254
	s_waitcnt lgkmcnt(0)
	s_add_u32 s2, s14, s16
	s_addc_u32 s16, s15, s17
	s_lshl_b64 s[14:15], s[26:27], 16
	s_add_u32 s20, s44, s14
	s_addc_u32 s21, s45, s15
	s_lshl_b32 s14, s84, 6
	s_and_b32 s17, s14, 0x1c0
	s_lshl_b32 s14, s17, 2
	s_add_u32 s14, s2, s14
	v_ashrrev_i32_e32 v0, 4, v15
	v_lshlrev_b32_e32 v16, 4, v15
	s_addc_u32 s15, s16, 0
	v_and_b32_e32 v2, 0xf0, v16
	v_mov_b32_e32 v3, v149
	v_ashrrev_i32_e32 v1, 31, v0
	v_lshl_add_u64 v[4:5], s[14:15], 0, v[2:3]
	v_lshlrev_b64 v[6:7], 11, v[0:1]
	v_lshl_add_u64 v[4:5], v[4:5], 0, v[6:7]
	s_waitcnt vmcnt(0)
	s_barrier
	v_mad_u64_u32 v[6:7], s[14:15], v0, s93, v[2:3]
	global_load_dwordx4 v[104:107], v[4:5], off
	s_mov_b32 s2, 0x8000
	v_and_b32_e32 v25, 48, v16
	v_ashrrev_i32_e32 v24, 2, v15
	v_add_co_u32_e32 v0, vcc, s2, v4
	s_mov_b32 s2, 0x10000
	s_nop 0
	v_addc_co_u32_e32 v1, vcc, 0, v5, vcc
	global_load_dwordx4 v[108:111], v[0:1], off
	v_add_co_u32_e32 v0, vcc, s2, v4
	s_nop 0
	v_addc_co_u32_e32 v1, vcc, 0, v5, vcc
	global_load_dwordx4 v[112:115], v[0:1], off
	s_mov_b32 s2, 0x18000
	v_add_co_u32_e32 v0, vcc, s2, v4
	s_nop 0
	v_addc_co_u32_e32 v1, vcc, 0, v5, vcc
	global_load_dwordx4 v[116:119], v[0:1], off
	v_add_u32_e32 v7, 0x1040, v6
	s_waitcnt vmcnt(3)
	ds_write2_b32 v6, v104, v105 offset1:1
	ds_write2_b32 v6, v106, v107 offset0:2 offset1:3
	s_waitcnt vmcnt(2)
	ds_write2_b32 v7, v108, v109 offset1:1
	v_add_u32_e32 v0, 0x1048, v6
	ds_write2_b32 v0, v110, v111 offset1:1
	v_add_u32_e32 v7, 0x2080, v6
	s_waitcnt vmcnt(1)
	ds_write2_b32 v7, v112, v113 offset1:1
	v_add_u32_e32 v0, 0x2088, v6
	ds_write2_b32 v0, v114, v115 offset1:1
	v_add_u32_e32 v7, 0x30c0, v6
	s_waitcnt vmcnt(0)
	ds_write2_b32 v7, v116, v117 offset1:1
	v_add_u32_e32 v0, 0x30c8, v6
	ds_write2_b32 v0, v118, v119 offset1:1
	v_and_b32_e32 v0, -4, v15
	v_mul_u32_u24_e32 v1, 0x41, v25
	v_lshl_add_u32 v2, v1, 2, v0
	s_waitcnt lgkmcnt(0)
	s_barrier
	ds_read2_b32 v[4:5], v2 offset1:65
	v_add_u32_e32 v3, 0x800, v2
	ds_read2_b32 v[16:17], v3 offset0:8 offset1:73
	ds_read2_b32 v[0:1], v2 offset0:130 offset1:195
	ds_read2_b32 v[18:19], v3 offset0:138 offset1:203
	v_add_u32_e32 v3, 0x400, v2
	ds_read2_b32 v[6:7], v3 offset0:4 offset1:69
	v_add_u32_e32 v15, 0xc00, v2
	ds_read2_b32 v[20:21], v15 offset0:12 offset1:77
	ds_read2_b32 v[2:3], v3 offset0:134 offset1:199
	ds_read2_b32 v[22:23], v15 offset0:142 offset1:207
	s_waitcnt lgkmcnt(5)
	v_cvt_pk_bf16_f32 v1, v0, v1
	v_cvt_pk_bf16_f32 v0, v4, v5
	v_cvt_pk_bf16_f32 v4, v16, v17
	v_add_u32_e32 v16, s17, v24
	v_ashrrev_i32_e32 v17, 31, v16
	v_lshlrev_b64 v[16:17], 7, v[16:17]
	s_waitcnt lgkmcnt(4)
	v_cvt_pk_bf16_f32 v5, v18, v19
	v_lshl_add_u64 v[16:17], s[20:21], 0, v[16:17]
	v_lshlrev_b32_e32 v18, 1, v25
	v_mov_b32_e32 v19, v149
	s_waitcnt lgkmcnt(1)
	v_cvt_pk_bf16_f32 v3, v2, v3
	v_cvt_pk_bf16_f32 v2, v6, v7
	v_lshl_add_u64 v[16:17], v[16:17], 0, v[18:19]
	s_waitcnt lgkmcnt(0)
	v_cvt_pk_bf16_f32 v7, v22, v23
	v_cvt_pk_bf16_f32 v6, v20, v21
	global_store_dwordx4 v[16:17], v[0:3], off
	global_store_dwordx4 v[16:17], v[4:7], off offset:16

.LBB0_644:
	s_andn2_b64 vcc, exec, s[14:15]
	s_cbranch_vccnz .LBB0_646
	s_load_dwordx2 s[14:15], s[4:5], 0x100
	s_lshl_b32 s2, s84, 2
	s_lshl_b32 s16, s84, 6
	s_add_i32 s2, s2, 0x3cb80
	s_and_b32 s16, s16, 0x3c0
	v_mov_b32_e32 v15, v254
	s_and_b32 s2, s2, 0x3ffc0
	s_lshl_b32 s17, s16, 2
	v_ashrrev_i32_e32 v16, 4, v15
	s_waitcnt lgkmcnt(0)
	s_add_u32 s14, s14, s17
	v_lshlrev_b32_e32 v18, 4, v15
	v_add_u32_e32 v6, s2, v16
	s_addc_u32 s15, s15, 0
	v_and_b32_e32 v0, 0xf0, v18
	v_mov_b32_e32 v1, v149
	v_ashrrev_i32_e32 v7, 31, v6
	v_lshl_add_u64 v[4:5], s[14:15], 0, v[0:1]
	v_lshlrev_b64 v[2:3], 12, v[6:7]
	v_lshl_add_u64 v[2:3], v[4:5], 0, v[2:3]
	s_waitcnt vmcnt(0)
	s_barrier
	v_mad_u64_u32 v[16:17], s[14:15], v16, s93, v[0:1]
	global_load_dwordx4 v[104:107], v[2:3], off
	v_and_b32_e32 v25, 48, v18
	v_ashrrev_i32_e32 v24, 2, v15
	s_lshl_b32 s26, s2, 1
	v_add_u32_e32 v0, 16, v6
	v_ashrrev_i32_e32 v1, 31, v0
	v_lshlrev_b64 v[0:1], 12, v[0:1]
	v_lshl_add_u64 v[0:1], v[4:5], 0, v[0:1]
	global_load_dwordx4 v[108:111], v[0:1], off
	v_add_u32_e32 v0, 32, v6
	v_ashrrev_i32_e32 v1, 31, v0
	v_lshlrev_b64 v[0:1], 12, v[0:1]
	v_lshl_add_u64 v[0:1], v[4:5], 0, v[0:1]
	global_load_dwordx4 v[112:115], v[0:1], off
	v_add_u32_e32 v0, 48, v6
	v_ashrrev_i32_e32 v1, 31, v0
	v_lshlrev_b64 v[0:1], 12, v[0:1]
	v_lshl_add_u64 v[0:1], v[4:5], 0, v[0:1]
	global_load_dwordx4 v[116:119], v[0:1], off
	v_add_u32_e32 v7, 0x1040, v16
	s_waitcnt vmcnt(3)
	ds_write2_b32 v16, v104, v105 offset1:1
	ds_write2_b32 v16, v106, v107 offset0:2 offset1:3
	s_waitcnt vmcnt(2)
	ds_write2_b32 v7, v108, v109 offset1:1
	v_add_u32_e32 v0, 0x1048, v16
	ds_write2_b32 v0, v110, v111 offset1:1
	v_add_u32_e32 v7, 0x2080, v16
	s_waitcnt vmcnt(1)
	ds_write2_b32 v7, v112, v113 offset1:1
	v_add_u32_e32 v0, 0x2088, v16
	ds_write2_b32 v0, v114, v115 offset1:1
	v_add_u32_e32 v4, 0x30c0, v16
	s_waitcnt vmcnt(0)
	ds_write2_b32 v4, v116, v117 offset1:1
	v_add_u32_e32 v0, 0x30c8, v16
	ds_write2_b32 v0, v118, v119 offset1:1
	v_and_b32_e32 v0, -4, v15
	v_mul_u32_u24_e32 v1, 0x41, v25
	v_lshl_add_u32 v2, v1, 2, v0
	s_waitcnt lgkmcnt(0)
	s_barrier
	ds_read2_b32 v[4:5], v2 offset1:65
	v_add_u32_e32 v3, 0x800, v2
	ds_read2_b32 v[16:17], v3 offset0:8 offset1:73
	ds_read2_b32 v[0:1], v2 offset0:130 offset1:195
	ds_read2_b32 v[18:19], v3 offset0:138 offset1:203
	v_add_u32_e32 v3, 0x400, v2
	ds_read2_b32 v[6:7], v3 offset0:4 offset1:69
	v_add_u32_e32 v15, 0xc00, v2
	s_waitcnt lgkmcnt(2)
	v_cvt_pk_bf16_f32 v1, v0, v1
	v_cvt_pk_bf16_f32 v0, v4, v5
	v_cvt_pk_bf16_f32 v4, v16, v17
	v_add_u32_e32 v16, s16, v24
	ds_read2_b32 v[20:21], v15 offset0:12 offset1:77
	ds_read2_b32 v[2:3], v3 offset0:134 offset1:199
	ds_read2_b32 v[22:23], v15 offset0:142 offset1:207
	v_ashrrev_i32_e32 v17, 31, v16
	v_lshlrev_b64 v[16:17], 13, v[16:17]
	v_lshl_add_u64 v[16:17], s[12:13], 0, v[16:17]
	s_waitcnt lgkmcnt(4)
	v_cvt_pk_bf16_f32 v5, v18, v19
	v_lshl_add_u64 v[16:17], v[16:17], 0, s[26:27]
	v_lshlrev_b32_e32 v18, 1, v25
	v_mov_b32_e32 v19, v149
	s_waitcnt lgkmcnt(1)
	v_cvt_pk_bf16_f32 v3, v2, v3
	v_cvt_pk_bf16_f32 v2, v6, v7
	v_lshl_add_u64 v[16:17], v[16:17], 0, v[18:19]
	s_waitcnt lgkmcnt(0)
	v_cvt_pk_bf16_f32 v7, v22, v23
	v_cvt_pk_bf16_f32 v6, v20, v21
	global_store_dwordx4 v[16:17], v[0:3], off
	global_store_dwordx4 v[16:17], v[4:7], off offset:16

.LBB0_647:
	s_andn2_b64 vcc, exec, s[14:15]
	s_cbranch_vccnz .LBB0_649
	s_load_dwordx2 s[14:15], s[4:5], 0xf8
	s_add_i32 s2, s84, 0xfffff6e0
	s_and_b32 s16, s2, 0xffc0
	s_lshl_b32 s2, s2, 6
	s_and_b32 s2, s2, 0xfc0
	v_mov_b32_e32 v15, v254
	s_lshl_b32 s17, s2, 2
	v_ashrrev_i32_e32 v16, 4, v15
	s_waitcnt lgkmcnt(0)
	s_add_u32 s14, s14, s17
	v_lshlrev_b32_e32 v18, 4, v15
	v_add_u32_e32 v6, s16, v16
	s_addc_u32 s15, s15, 0
	v_and_b32_e32 v0, 0xf0, v18
	v_mov_b32_e32 v1, v149
	v_ashrrev_i32_e32 v7, 31, v6
	v_lshl_add_u64 v[4:5], s[14:15], 0, v[0:1]
	v_lshlrev_b64 v[2:3], 14, v[6:7]
	v_lshl_add_u64 v[2:3], v[4:5], 0, v[2:3]
	s_waitcnt vmcnt(0)
	s_barrier
	v_mad_u64_u32 v[16:17], s[14:15], v16, s93, v[0:1]
	global_load_dwordx4 v[104:107], v[2:3], off
	v_and_b32_e32 v25, 48, v18
	v_ashrrev_i32_e32 v24, 2, v15
	s_lshl_b32 s26, s16, 1
	v_add_u32_e32 v0, 16, v6
	v_ashrrev_i32_e32 v1, 31, v0
	v_lshlrev_b64 v[0:1], 14, v[0:1]
	v_lshl_add_u64 v[0:1], v[4:5], 0, v[0:1]
	global_load_dwordx4 v[108:111], v[0:1], off
	v_add_u32_e32 v0, 32, v6
	v_ashrrev_i32_e32 v1, 31, v0
	v_lshlrev_b64 v[0:1], 14, v[0:1]
	v_lshl_add_u64 v[0:1], v[4:5], 0, v[0:1]
	global_load_dwordx4 v[112:115], v[0:1], off
	v_add_u32_e32 v0, 48, v6
	v_ashrrev_i32_e32 v1, 31, v0
	v_lshlrev_b64 v[0:1], 14, v[0:1]
	v_lshl_add_u64 v[0:1], v[4:5], 0, v[0:1]
	global_load_dwordx4 v[116:119], v[0:1], off
	v_add_u32_e32 v7, 0x1040, v16
	s_waitcnt vmcnt(3)
	ds_write2_b32 v16, v104, v105 offset1:1
	ds_write2_b32 v16, v106, v107 offset0:2 offset1:3
	s_waitcnt vmcnt(2)
	ds_write2_b32 v7, v108, v109 offset1:1
	v_add_u32_e32 v0, 0x1048, v16
	ds_write2_b32 v0, v110, v111 offset1:1
	v_add_u32_e32 v7, 0x2080, v16
	s_waitcnt vmcnt(1)
	ds_write2_b32 v7, v112, v113 offset1:1
	v_add_u32_e32 v0, 0x2088, v16
	ds_write2_b32 v0, v114, v115 offset1:1
	v_add_u32_e32 v4, 0x30c0, v16
	s_waitcnt vmcnt(0)
	ds_write2_b32 v4, v116, v117 offset1:1
	v_add_u32_e32 v0, 0x30c8, v16
	ds_write2_b32 v0, v118, v119 offset1:1
	v_and_b32_e32 v0, -4, v15
	v_mul_u32_u24_e32 v1, 0x41, v25
	v_lshl_add_u32 v2, v1, 2, v0
	s_waitcnt lgkmcnt(0)
	s_barrier
	ds_read2_b32 v[4:5], v2 offset1:65
	v_add_u32_e32 v3, 0x800, v2
	ds_read2_b32 v[16:17], v3 offset0:8 offset1:73
	ds_read2_b32 v[0:1], v2 offset0:130 offset1:195
	ds_read2_b32 v[18:19], v3 offset0:138 offset1:203
	v_add_u32_e32 v3, 0x400, v2
	ds_read2_b32 v[6:7], v3 offset0:4 offset1:69
	v_add_u32_e32 v15, 0xc00, v2
	s_waitcnt lgkmcnt(2)
	v_cvt_pk_bf16_f32 v1, v0, v1
	v_cvt_pk_bf16_f32 v0, v4, v5
	v_cvt_pk_bf16_f32 v4, v16, v17
	v_add_u32_e32 v16, s2, v24
	ds_read2_b32 v[20:21], v15 offset0:12 offset1:77
	ds_read2_b32 v[2:3], v3 offset0:134 offset1:199
	ds_read2_b32 v[22:23], v15 offset0:142 offset1:207
	v_ashrrev_i32_e32 v17, 31, v16
	v_lshlrev_b64 v[16:17], 11, v[16:17]
	v_lshl_add_u64 v[16:17], s[8:9], 0, v[16:17]
	s_waitcnt lgkmcnt(4)
	v_cvt_pk_bf16_f32 v5, v18, v19
	v_lshl_add_u64 v[16:17], v[16:17], 0, s[26:27]
	v_lshlrev_b32_e32 v18, 1, v25
	v_mov_b32_e32 v19, v149
	s_waitcnt lgkmcnt(1)
	v_cvt_pk_bf16_f32 v3, v2, v3
	v_cvt_pk_bf16_f32 v2, v6, v7
	v_lshl_add_u64 v[16:17], v[16:17], 0, v[18:19]
	s_waitcnt lgkmcnt(0)
	v_cvt_pk_bf16_f32 v7, v22, v23
	v_cvt_pk_bf16_f32 v6, v20, v21
	global_store_dwordx4 v[16:17], v[0:3], off
	global_store_dwordx4 v[16:17], v[4:7], off offset:16

.LBB0_650:
	s_andn2_b64 vcc, exec, s[14:15]
	s_cbranch_vccnz .LBB0_652
	s_load_dwordx2 s[14:15], s[4:5], 0xe0
	s_lshl_b32 s2, s84, 2
	s_lshl_b32 s16, s84, 6
	s_addk_i32 s2, 0x380
	s_and_b32 s16, s16, 0x3c0
	v_mov_b32_e32 v15, v254
	s_and_b32 s2, s2, 0x3c0
	s_lshl_b32 s17, s16, 2
	v_ashrrev_i32_e32 v16, 4, v15
	s_waitcnt lgkmcnt(0)
	s_add_u32 s14, s14, s17
	v_lshlrev_b32_e32 v18, 4, v15
	v_add_u32_e32 v6, s2, v16
	s_addc_u32 s15, s15, 0
	v_and_b32_e32 v0, 0xf0, v18
	v_mov_b32_e32 v1, v149
	v_ashrrev_i32_e32 v7, 31, v6
	v_lshl_add_u64 v[4:5], s[14:15], 0, v[0:1]
	v_lshlrev_b64 v[2:3], 12, v[6:7]
	v_lshl_add_u64 v[2:3], v[4:5], 0, v[2:3]
	s_waitcnt vmcnt(0)
	s_barrier
	v_mad_u64_u32 v[16:17], s[14:15], v16, s93, v[0:1]
	global_load_dwordx4 v[104:107], v[2:3], off
	v_and_b32_e32 v25, 48, v18
	v_ashrrev_i32_e32 v24, 2, v15
	s_lshl_b32 s26, s2, 1
	v_add_u32_e32 v0, 16, v6
	v_ashrrev_i32_e32 v1, 31, v0
	v_lshlrev_b64 v[0:1], 12, v[0:1]
	v_lshl_add_u64 v[0:1], v[4:5], 0, v[0:1]
	global_load_dwordx4 v[108:111], v[0:1], off
	v_add_u32_e32 v0, 32, v6
	v_ashrrev_i32_e32 v1, 31, v0
	v_lshlrev_b64 v[0:1], 12, v[0:1]
	v_lshl_add_u64 v[0:1], v[4:5], 0, v[0:1]
	global_load_dwordx4 v[112:115], v[0:1], off
	v_add_u32_e32 v0, 48, v6
	v_ashrrev_i32_e32 v1, 31, v0
	v_lshlrev_b64 v[0:1], 12, v[0:1]
	v_lshl_add_u64 v[0:1], v[4:5], 0, v[0:1]
	global_load_dwordx4 v[116:119], v[0:1], off
	v_add_u32_e32 v7, 0x1040, v16
	s_waitcnt vmcnt(3)
	ds_write2_b32 v16, v104, v105 offset1:1
	ds_write2_b32 v16, v106, v107 offset0:2 offset1:3
	s_waitcnt vmcnt(2)
	ds_write2_b32 v7, v108, v109 offset1:1
	v_add_u32_e32 v0, 0x1048, v16
	ds_write2_b32 v0, v110, v111 offset1:1
	v_add_u32_e32 v7, 0x2080, v16
	s_waitcnt vmcnt(1)
	ds_write2_b32 v7, v112, v113 offset1:1
	v_add_u32_e32 v0, 0x2088, v16
	ds_write2_b32 v0, v114, v115 offset1:1
	v_add_u32_e32 v4, 0x30c0, v16
	s_waitcnt vmcnt(0)
	ds_write2_b32 v4, v116, v117 offset1:1
	v_add_u32_e32 v0, 0x30c8, v16
	ds_write2_b32 v0, v118, v119 offset1:1
	v_and_b32_e32 v0, -4, v15
	v_mul_u32_u24_e32 v1, 0x41, v25
	v_lshl_add_u32 v2, v1, 2, v0
	s_waitcnt lgkmcnt(0)
	s_barrier
	ds_read2_b32 v[4:5], v2 offset1:65
	v_add_u32_e32 v3, 0x800, v2
	ds_read2_b32 v[16:17], v3 offset0:8 offset1:73
	ds_read2_b32 v[0:1], v2 offset0:130 offset1:195
	ds_read2_b32 v[18:19], v3 offset0:138 offset1:203
	v_add_u32_e32 v3, 0x400, v2
	ds_read2_b32 v[6:7], v3 offset0:4 offset1:69
	v_add_u32_e32 v15, 0xc00, v2
	s_waitcnt lgkmcnt(2)
	v_cvt_pk_bf16_f32 v1, v0, v1
	v_cvt_pk_bf16_f32 v0, v4, v5
	v_cvt_pk_bf16_f32 v4, v16, v17
	v_add_u32_e32 v16, s16, v24
	ds_read2_b32 v[20:21], v15 offset0:12 offset1:77
	ds_read2_b32 v[2:3], v3 offset0:134 offset1:199
	ds_read2_b32 v[22:23], v15 offset0:142 offset1:207
	v_ashrrev_i32_e32 v17, 31, v16
	v_lshlrev_b64 v[16:17], 11, v[16:17]
	v_lshl_add_u64 v[16:17], s[28:29], 0, v[16:17]
	s_waitcnt lgkmcnt(4)
	v_cvt_pk_bf16_f32 v5, v18, v19
	v_lshl_add_u64 v[16:17], v[16:17], 0, s[26:27]
	v_lshlrev_b32_e32 v18, 1, v25
	v_mov_b32_e32 v19, v149
	s_waitcnt lgkmcnt(1)
	v_cvt_pk_bf16_f32 v3, v2, v3
	v_cvt_pk_bf16_f32 v2, v6, v7
	v_lshl_add_u64 v[16:17], v[16:17], 0, v[18:19]
	s_waitcnt lgkmcnt(0)
	v_cvt_pk_bf16_f32 v7, v22, v23
	v_cvt_pk_bf16_f32 v6, v20, v21
	global_store_dwordx4 v[16:17], v[0:3], off
	global_store_dwordx4 v[16:17], v[4:7], off offset:16

.LBB0_653:
	s_andn2_b64 vcc, exec, s[14:15]
	s_cbranch_vccnz .LBB0_655
	s_load_dwordx2 s[14:15], s[4:5], 0xd8
	s_add_i32 s2, s84, 0xfffff960
	s_lshr_b32 s26, s2, 7
	s_lshl_b64 s[16:17], s[26:27], 21
	v_mov_b32_e32 v15, v254
	s_waitcnt lgkmcnt(0)
	s_add_u32 s16, s14, s16
	s_addc_u32 s17, s15, s17
	s_lshl_b64 s[14:15], s[26:27], 20
	s_add_u32 s20, s82, s14
	s_addc_u32 s21, s83, s15
	s_lshl_b32 s14, s84, 6
	s_lshl_b32 s2, s2, 2
	s_and_b32 s22, s14, 0x3c0
	s_and_b32 s2, s2, 0x1c0
	s_lshl_b32 s14, s22, 2
	v_ashrrev_i32_e32 v16, 4, v15
	s_add_u32 s14, s16, s14
	v_lshlrev_b32_e32 v18, 4, v15
	v_add_u32_e32 v6, s2, v16
	s_addc_u32 s15, s17, 0
	v_and_b32_e32 v0, 0xf0, v18
	v_mov_b32_e32 v1, v149
	v_ashrrev_i32_e32 v7, 31, v6
	v_lshl_add_u64 v[4:5], s[14:15], 0, v[0:1]
	v_lshlrev_b64 v[2:3], 12, v[6:7]
	v_lshl_add_u64 v[2:3], v[4:5], 0, v[2:3]
	s_waitcnt vmcnt(0)
	s_barrier
	v_mad_u64_u32 v[16:17], s[14:15], v16, s93, v[0:1]
	global_load_dwordx4 v[104:107], v[2:3], off
	v_and_b32_e32 v25, 48, v18
	v_ashrrev_i32_e32 v24, 2, v15
	s_lshl_b32 s26, s2, 1
	v_add_u32_e32 v0, 16, v6
	v_ashrrev_i32_e32 v1, 31, v0
	v_lshlrev_b64 v[0:1], 12, v[0:1]
	v_lshl_add_u64 v[0:1], v[4:5], 0, v[0:1]
	global_load_dwordx4 v[108:111], v[0:1], off
	v_add_u32_e32 v0, 32, v6
	v_ashrrev_i32_e32 v1, 31, v0
	v_lshlrev_b64 v[0:1], 12, v[0:1]
	v_lshl_add_u64 v[0:1], v[4:5], 0, v[0:1]
	global_load_dwordx4 v[112:115], v[0:1], off
	v_add_u32_e32 v0, 48, v6
	v_ashrrev_i32_e32 v1, 31, v0
	v_lshlrev_b64 v[0:1], 12, v[0:1]
	v_lshl_add_u64 v[0:1], v[4:5], 0, v[0:1]
	global_load_dwordx4 v[116:119], v[0:1], off
	v_add_u32_e32 v7, 0x1040, v16
	s_waitcnt vmcnt(3)
	ds_write2_b32 v16, v104, v105 offset1:1
	ds_write2_b32 v16, v106, v107 offset0:2 offset1:3
	s_waitcnt vmcnt(2)
	ds_write2_b32 v7, v108, v109 offset1:1
	v_add_u32_e32 v0, 0x1048, v16
	ds_write2_b32 v0, v110, v111 offset1:1
	v_add_u32_e32 v7, 0x2080, v16
	s_waitcnt vmcnt(1)
	ds_write2_b32 v7, v112, v113 offset1:1
	v_add_u32_e32 v0, 0x2088, v16
	ds_write2_b32 v0, v114, v115 offset1:1
	v_add_u32_e32 v4, 0x30c0, v16
	s_waitcnt vmcnt(0)
	ds_write2_b32 v4, v116, v117 offset1:1
	v_add_u32_e32 v0, 0x30c8, v16
	ds_write2_b32 v0, v118, v119 offset1:1
	v_and_b32_e32 v0, -4, v15
	v_mul_u32_u24_e32 v1, 0x41, v25
	v_lshl_add_u32 v2, v1, 2, v0
	s_waitcnt lgkmcnt(0)
	s_barrier
	ds_read2_b32 v[4:5], v2 offset1:65
	v_add_u32_e32 v3, 0x800, v2
	ds_read2_b32 v[16:17], v3 offset0:8 offset1:73
	ds_read2_b32 v[0:1], v2 offset0:130 offset1:195
	ds_read2_b32 v[18:19], v3 offset0:138 offset1:203
	v_add_u32_e32 v3, 0x400, v2
	ds_read2_b32 v[6:7], v3 offset0:4 offset1:69
	v_add_u32_e32 v15, 0xc00, v2
	s_waitcnt lgkmcnt(2)
	v_cvt_pk_bf16_f32 v1, v0, v1
	v_cvt_pk_bf16_f32 v0, v4, v5
	v_cvt_pk_bf16_f32 v4, v16, v17
	v_add_u32_e32 v16, s22, v24
	ds_read2_b32 v[20:21], v15 offset0:12 offset1:77
	ds_read2_b32 v[2:3], v3 offset0:134 offset1:199
	ds_read2_b32 v[22:23], v15 offset0:142 offset1:207
	v_ashrrev_i32_e32 v17, 31, v16
	v_lshlrev_b64 v[16:17], 10, v[16:17]
	v_lshl_add_u64 v[16:17], s[20:21], 0, v[16:17]
	s_waitcnt lgkmcnt(4)
	v_cvt_pk_bf16_f32 v5, v18, v19
	v_lshl_add_u64 v[16:17], v[16:17], 0, s[26:27]
	v_lshlrev_b32_e32 v18, 1, v25
	v_mov_b32_e32 v19, v149
	s_waitcnt lgkmcnt(1)
	v_cvt_pk_bf16_f32 v3, v2, v3
	v_cvt_pk_bf16_f32 v2, v6, v7
	v_lshl_add_u64 v[16:17], v[16:17], 0, v[18:19]
	s_waitcnt lgkmcnt(0)
	v_cvt_pk_bf16_f32 v7, v22, v23
	v_cvt_pk_bf16_f32 v6, v20, v21
	global_store_dwordx4 v[16:17], v[0:3], off
	global_store_dwordx4 v[16:17], v[4:7], off offset:16

.LBB0_656:
	s_mul_hi_i32 s2, s84, 0x4d4873ed
	s_lshr_b32 s16, s2, 31
	s_ashr_i32 s2, s2, 5
	s_add_i32 s2, s2, s16
	s_load_dwordx2 s[14:15], s[4:5], 0x48
	s_lshl_b32 s20, s2, 6
	s_mulk_i32 s2, 0x6a
	s_sub_i32 s2, s84, s2
	s_lshl_b32 s22, s2, 6
	s_ashr_i32 s23, s22, 31
	v_mov_b32_e32 v15, v254
	s_lshl_b64 s[16:17], s[22:23], 2
	s_waitcnt lgkmcnt(0)
	s_add_u32 s14, s14, s16
	v_lshlrev_b32_e32 v16, 4, v15
	v_ashrrev_i32_e32 v6, 4, v15
	s_addc_u32 s15, s15, s17
	v_and_b32_e32 v0, 0xf0, v16
	v_mov_b32_e32 v1, v149
	v_lshl_add_u64 v[4:5], s[14:15], 0, v[0:1]
	v_add_u32_e32 v17, s20, v6
	s_movk_i32 s2, 0x6a00
	v_mad_i64_i32 v[2:3], s[14:15], v17, s2, v[4:5]
	s_waitcnt vmcnt(0)
	s_barrier
	v_mad_u64_u32 v[6:7], s[14:15], v6, s93, v[0:1]
	global_load_dwordx4 v[104:107], v[2:3], off
	v_and_b32_e32 v25, 48, v16
	v_ashrrev_i32_e32 v24, 2, v15
	s_ashr_i32 s21, s20, 31
	v_add_u32_e32 v0, 16, v17
	v_mad_i64_i32 v[0:1], s[14:15], v0, s2, v[4:5]
	global_load_dwordx4 v[108:111], v[0:1], off
	v_add_u32_e32 v0, 32, v17
	v_mad_i64_i32 v[0:1], s[14:15], v0, s2, v[4:5]
	global_load_dwordx4 v[112:115], v[0:1], off
	v_add_u32_e32 v0, 48, v17
	v_mad_i64_i32 v[0:1], s[14:15], v0, s2, v[4:5]
	global_load_dwordx4 v[116:119], v[0:1], off
	v_add_u32_e32 v7, 0x1040, v6
	s_waitcnt vmcnt(3)
	ds_write2_b32 v6, v104, v105 offset1:1
	ds_write2_b32 v6, v106, v107 offset0:2 offset1:3
	s_waitcnt vmcnt(2)
	ds_write2_b32 v7, v108, v109 offset1:1
	v_add_u32_e32 v0, 0x1048, v6
	ds_write2_b32 v0, v110, v111 offset1:1
	v_add_u32_e32 v7, 0x2080, v6
	s_waitcnt vmcnt(1)
	ds_write2_b32 v7, v112, v113 offset1:1
	v_add_u32_e32 v0, 0x2088, v6
	ds_write2_b32 v0, v114, v115 offset1:1
	v_add_u32_e32 v4, 0x30c0, v6
	s_waitcnt vmcnt(0)
	ds_write2_b32 v4, v116, v117 offset1:1
	v_add_u32_e32 v0, 0x30c8, v6
	ds_write2_b32 v0, v118, v119 offset1:1
	v_and_b32_e32 v0, -4, v15
	v_mul_u32_u24_e32 v1, 0x41, v25
	v_lshl_add_u32 v2, v1, 2, v0
	s_waitcnt lgkmcnt(0)
	s_barrier
	ds_read2_b32 v[4:5], v2 offset1:65
	v_add_u32_e32 v3, 0x800, v2
	ds_read2_b32 v[16:17], v3 offset0:8 offset1:73
	ds_read2_b32 v[0:1], v2 offset0:130 offset1:195
	ds_read2_b32 v[18:19], v3 offset0:138 offset1:203
	v_add_u32_e32 v3, 0x400, v2
	ds_read2_b32 v[6:7], v3 offset0:4 offset1:69
	v_add_u32_e32 v15, 0xc00, v2
	s_waitcnt lgkmcnt(2)
	v_cvt_pk_bf16_f32 v1, v0, v1
	v_cvt_pk_bf16_f32 v0, v4, v5
	v_cvt_pk_bf16_f32 v4, v16, v17
	v_add_u32_e32 v16, s22, v24
	ds_read2_b32 v[20:21], v15 offset0:12 offset1:77
	ds_read2_b32 v[2:3], v3 offset0:134 offset1:199
	ds_read2_b32 v[22:23], v15 offset0:142 offset1:207
	v_ashrrev_i32_e32 v17, 31, v16
	v_lshlrev_b64 v[16:17], 11, v[16:17]
	v_lshl_add_u64 v[16:17], s[30:31], 0, v[16:17]
	s_waitcnt lgkmcnt(4)
	v_cvt_pk_bf16_f32 v5, v18, v19
	v_lshl_add_u64 v[16:17], s[20:21], 1, v[16:17]
	v_lshlrev_b32_e32 v18, 1, v25
	v_mov_b32_e32 v19, v149
	s_waitcnt lgkmcnt(1)
	v_cvt_pk_bf16_f32 v3, v2, v3
	v_cvt_pk_bf16_f32 v2, v6, v7
	v_lshl_add_u64 v[16:17], v[16:17], 0, v[18:19]
	s_waitcnt lgkmcnt(0)
	v_cvt_pk_bf16_f32 v7, v22, v23
	v_cvt_pk_bf16_f32 v6, v20, v21
	global_store_dwordx4 v[16:17], v[0:3], off
	global_store_dwordx4 v[16:17], v[4:7], off offset:16
	s_branch .LBB0_613
